# diff item prologue: first K/V tile, bias-table slice and bound gain vectors requested with the first load batch
# speedup vs baseline: 1.0034x; 1.0034x over previous
; __device__ __forceinline__ float bflo(unsigned u) { return __uint_as_float(u << 16); }
; __device__ __forceinline__ float bfhi(unsigned u) { return __uint_as_float(u & 0xffff0000u); }
; template <int MODE>
; __device__ __forceinline__ void attn_item(const AttnP& p, int b, int h, int qb, LAS unsigned char* lds) {
;     ...
;     const int tok0 = b * SEQ, q0 = qb * 256, qw = q0 + 32 * w, qrow = qw + ln;
;     const bf16_t* P = p.P;
;     bf16x8 Qf[NC][4];
; #pragma unroll
;     for (int c = 0; c < NC; ++c) {
;         u32x4 raw[4]; float ss = 0.f;
; #pragma unroll
;         for (int ks = 0; ks < 4; ++ks) {
;             raw[ks] = *(const u32x4*)(P + (size_t)(tok0 + qrow) * PP + qcol + c * 64 + ks * 16 + hh * 8);
; #pragma unroll
;             for (int e = 0; e < 4; ++e) { const float lo = bflo(raw[ks][e]), hi = bfhi(raw[ks][e]); ss += lo * lo + hi * hi; }
;         }
;         float sc = 0.125f * LOG2E;
;         if (MODE != 1) { ss += __shfl_xor(ss, 32); sc *= 1.0f / sqrtf(ss * (1.0f / 64.0f) + 1e-6f); }
.LBB0_491:
	s_and_b64 vcc, exec, s[0:1]
	s_cbranch_vccz .LBB0_468
	v_mov_b32_e32 v50, v210
	s_ashr_i32 s2, s57, 5
	s_sub_i32 s5, 15, s2
	v_readfirstlane_b32 s0, v50
	s_ashr_i32 s7, s0, 6
	s_lshl_b32 s0, s57, 10
	s_and_b32 s8, s0, 0x7000
	s_lshl_b32 s0, s5, 8
	s_lshl_b32 s3, s7, 5
	v_and_b32_e32 v49, 31, v50
	s_add_i32 s4, s3, s0
	v_or_b32_e32 v228, s4, v49
	s_and_b32 s6, s57, 3
	v_add_u32_e32 v0, s8, v228
	v_mov_b64_e32 v[2:3], s[46:47]
	v_bfe_u32 v48, v50, 5, 1
	v_mad_i64_i32 v[2:3], s[0:1], v0, s76, v[2:3]
	s_lshl_b32 s92, s6, 8
	v_lshl_add_u64 v[2:3], v[2:3], 0, s[92:93]
	v_lshlrev_b32_e32 v206, 4, v48
	v_mov_b32_e32 v207, v1
	v_and_b32_e32 v0, 32, v50
	v_lshl_add_u64 v[32:33], v[2:3], 0, v[206:207]
	global_load_dwordx4 v[52:55], v0, s[40:41] offset:16
	global_load_dwordx4 v[34:37], v0, s[40:41]
	global_load_dwordx4 v[56:59], v0, s[40:41] offset:272
	global_load_dwordx4 v[38:41], v0, s[40:41] offset:256
	global_load_dwordx4 v[60:63], v[32:33], off offset:64
	global_load_dwordx4 v[64:67], v[32:33], off offset:96
	global_load_dwordx4 v[68:71], v[32:33], off
	global_load_dwordx4 v[72:75], v[32:33], off offset:32
	global_load_dwordx4 v[14:17], v0, s[40:41] offset:80
	global_load_dwordx4 v[22:25], v0, s[40:41] offset:64
	global_load_dwordx4 v[76:79], v0, s[40:41] offset:336
	global_load_dwordx4 v[80:83], v0, s[40:41] offset:320
	global_load_dwordx4 v[2:5], v0, s[40:41] offset:144
	global_load_dwordx4 v[10:13], v0, s[40:41] offset:128
	global_load_dwordx4 v[6:9], v0, s[40:41] offset:400
	global_load_dwordx4 v[18:21], v0, s[40:41] offset:384
	global_load_dwordx4 v[130:133], v0, s[40:41] offset:208
	global_load_dwordx4 v[134:137], v0, s[40:41] offset:192
	global_load_dwordx4 v[138:141], v0, s[40:41] offset:464
	global_load_dwordx4 v[142:145], v0, s[40:41] offset:448
	global_load_dwordx4 v[146:149], v[32:33], off offset:192
	global_load_dwordx4 v[150:153], v[32:33], off offset:224
	global_load_dwordx4 v[154:157], v[32:33], off offset:128
	global_load_dwordx4 v[158:161], v[32:33], off offset:160
	s_lshl_b32 s100, s5, 2
	s_or_b32 s100, s100, 3
	s_lshl_b32 s100, s100, 6
	v_ashrrev_i32_e32 v196, 3, v50
	v_add_u32_e32 v196, s8, v196
	v_add_u32_e32 v196, s100, v196
	v_mov_b64_e32 v[198:199], s[46:47]
	v_mad_i64_i32 v[198:199], s[100:101], v196, s76, v[198:199]
	v_lshlrev_b32_e32 v197, 3, v50
	v_and_b32_e32 v197, 56, v197
	v_lshlrev_b32_e32 v200, 1, v197
	v_mov_b32_e32 v201, 0
	s_lshl_b32 s100, s6, 8
	v_add_u32_e32 v200, s100, v200
	v_lshl_add_u64 v[198:199], v[198:199], 0, v[200:201]
	global_load_dwordx4 v[178:181], v[198:199], off offset:1024
	global_load_dwordx4 v[182:185], v[198:199], off offset:1152
	global_load_dwordx4 v[186:189], v[198:199], off offset:2048
	global_load_dwordx4 v[190:193], v[198:199], off offset:2176
	v_lshl_add_u32 v202, s6, 8, v50
	v_lshlrev_b32_e32 v202, 2, v202
	global_load_dword v194, v202, s[42:43]
	v_and_b32_e32 v203, 63, v50
	v_lshlrev_b32_e32 v203, 2, v203
	global_load_dword v195, v203, s[40:41]
	global_load_dword v204, v203, s[40:41] offset:256
	s_lshl_b32 s0, s7, 13
	v_and_b32_e32 v51, 63, v50
	s_add_i32 s0, s0, 0
	s_mov_b32 s7, 0xf800000
	s_add_i32 s0, s0, 0x13000
	s_mov_b32 s74, 0xf800000
	s_lshl_b32 s9, s6, 7
	s_waitcnt vmcnt(0)
	v_pk_mul_f32 v[14:15], v[14:15], v[76:77]
	s_waitcnt lgkmcnt(0)
	v_lshlrev_b32_e32 v45, 16, v63
	v_lshlrev_b32_e32 v44, 16, v62
	v_lshlrev_b32_e32 v84, 16, v71
	v_and_b32_e32 v85, 0xffff0000, v71
	v_lshlrev_b32_e32 v86, 16, v70
	v_and_b32_e32 v87, 0xffff0000, v70
	v_lshlrev_b32_e32 v70, 16, v69
	v_and_b32_e32 v71, 0xffff0000, v69
	v_lshlrev_b32_e32 v88, 16, v68
	v_and_b32_e32 v89, 0xffff0000, v68
	v_pk_mul_f32 v[28:29], v[36:37], v[40:41]
	v_pk_mul_f32 v[30:31], v[34:35], v[38:39]
	v_and_b32_e32 v47, 0xffff0000, v63
	v_and_b32_e32 v46, 0xffff0000, v62
	v_lshlrev_b32_e32 v39, 16, v67
	v_lshlrev_b32_e32 v38, 16, v66
	v_and_b32_e32 v37, 0xffff0000, v67
	v_and_b32_e32 v36, 0xffff0000, v66
	v_pk_mul_f32 v[62:63], v[84:85], v[84:85]
	v_pk_mul_f32 v[66:67], v[70:71], v[70:71]
	v_pk_mul_f32 v[96:97], v[88:89], v[88:89]
	v_lshlrev_b32_e32 v43, 16, v65
	v_lshlrev_b32_e32 v42, 16, v64
	v_and_b32_e32 v41, 0xffff0000, v65
	v_and_b32_e32 v40, 0xffff0000, v64
	v_pk_mul_f32 v[64:65], v[86:87], v[86:87]
	v_add_f32_e32 v62, v62, v63
	v_add_f32_e32 v63, v66, v67
	v_add_f32_e32 v66, v96, v97
	v_lshlrev_b32_e32 v92, 16, v72
	v_and_b32_e32 v93, 0xffff0000, v72
	v_add_f32_e32 v63, v66, v63
	v_add_f32_e32 v64, v64, v65
	v_lshlrev_b32_e32 v68, 16, v75
	v_and_b32_e32 v69, 0xffff0000, v75
	v_lshlrev_b32_e32 v90, 16, v74
	v_and_b32_e32 v91, 0xffff0000, v74
	v_lshlrev_b32_e32 v74, 16, v73
	v_and_b32_e32 v75, 0xffff0000, v73
	v_pk_mul_f32 v[104:105], v[92:93], v[92:93]
	v_add_f32_e32 v63, v64, v63
	v_pk_mul_f32 v[102:103], v[74:75], v[74:75]
	v_add_f32_e32 v62, v62, v63
	v_add_f32_e32 v63, v104, v105
	v_pk_mul_f32 v[100:101], v[90:91], v[90:91]
	v_add_f32_e32 v62, v63, v62
	v_add_f32_e32 v63, v102, v103
	v_lshlrev_b32_e32 v94, 16, v60
	v_pk_mul_f32 v[98:99], v[68:69], v[68:69]
	v_and_b32_e32 v95, 0xffff0000, v60
	v_add_f32_e32 v62, v63, v62
	v_add_f32_e32 v63, v100, v101
	v_lshlrev_b32_e32 v72, 16, v61
	v_and_b32_e32 v73, 0xffff0000, v61
	v_pk_mul_f32 v[60:61], v[94:95], v[94:95]
	v_add_f32_e32 v62, v63, v62
	v_add_f32_e32 v63, v98, v99
	v_pk_mul_f32 v[106:107], v[72:73], v[72:73]
	v_add_f32_e32 v62, v63, v62
	v_add_f32_e32 v60, v60, v61
	v_pk_mul_f32 v[34:35], v[46:47], v[46:47]
	v_add_f32_e32 v60, v60, v62
	v_add_f32_e32 v61, v106, v107
	v_pk_fma_f32 v[34:35], v[44:45], v[44:45], v[34:35]
	v_add_f32_e32 v60, v61, v60
	v_pk_mul_f32 v[26:27], v[52:53], v[56:57]
	v_pk_mul_f32 v[52:53], v[40:41], v[40:41]
	v_add_f32_e32 v34, v34, v60
	v_pk_fma_f32 v[52:53], v[42:43], v[42:43], v[52:53]
	v_add_f32_e32 v34, v35, v34
	v_pk_mul_f32 v[56:57], v[36:37], v[36:37]
	v_add_f32_e32 v34, v52, v34
	v_pk_fma_f32 v[56:57], v[38:39], v[38:39], v[56:57]
	v_add_f32_e32 v34, v53, v34
	v_add_f32_e32 v34, v56, v34
	v_add_f32_e32 v52, v57, v34
	ds_bpermute_b32 v53, v226, v52
	v_pk_mul_f32 v[34:35], v[54:55], v[58:59]
	v_lshlrev_b32_e32 v54, 4, v51
	v_add_u32_e32 v207, s0, v54
	v_pk_mul_f32 v[24:25], v[24:25], v[82:83]
	s_waitcnt lgkmcnt(0)
; #define LAS __attribute__((address_space(3)))
; __device__ __forceinline__ unsigned pk2(float lo, float hi) { f32x2 v = {lo, hi}; bf16x2_t b = __builtin_convertvector(v, bf16x2_t); return __builtin_bit_cast(unsigned, b); }
; __device__ __forceinline__ float bflo(unsigned u) { return __uint_as_float(u << 16); }
; __device__ __forceinline__ float bfhi(unsigned u) { return __uint_as_float(u & 0xffff0000u); }
; template <int MODE>
; __device__ __forceinline__ void attn_item(const AttnP& p, int b, int h, int qb, LAS unsigned char* lds) {
;     ...
;         float sc = 0.125f * LOG2E;
;         if (MODE != 1) { ss += __shfl_xor(ss, 32); sc *= 1.0f / sqrtf(ss * (1.0f / 64.0f) + 1e-6f); }
; #pragma unroll
;         for (int ks = 0; ks < 4; ++ks) {
;             u32x4 o;
; #pragma unroll
;             for (int e = 0; e < 4; ++e) {
;                 float lo = bflo(raw[ks][e]) * sc, hi = bfhi(raw[ks][e]) * sc;
;                 if (MODE != 1) {
;                     const int d = ks * 16 + hh * 8 + 2 * e;
;                     const float* gq = p.qk_gain + ((MODE == 0) ? 0 : 128); const float* gk = gq + 64;
;                     lo *= gq[d] * gk[d]; hi *= gq[d + 1] * gk[d + 1];
;                 }
;                 o[e] = pk2(lo, hi);
;             }
;             Qf[c][ks] = __builtin_bit_cast(bf16x8, o);
;             if (QPARK) *(LAS u32x4*)(lds + QP_OFF + w * 8192 + ((c * 4 + ks) * 64 + lane) * 16) = o;
;         }
	v_add_f32_e32 v52, v52, v53
	v_fmamk_f32 v52, v52, 0x3c800000, v211
	v_mul_f32_e32 v53, 0x4f800000, v52
	v_cmp_gt_f32_e32 vcc, s7, v52
	v_pk_mul_f32 v[10:11], v[10:11], v[18:19]
	v_pk_mul_f32 v[16:17], v[16:17], v[78:79]
	v_cndmask_b32_e32 v76, v52, v53, vcc
	v_mov_b64_e32 v[52:53], v[130:131]
	v_mov_b64_e32 v[54:55], v[132:133]
	v_mov_b64_e32 v[56:57], v[134:135]
	v_mov_b64_e32 v[58:59], v[136:137]
	v_mov_b64_e32 v[60:61], v[138:139]
	v_mov_b64_e32 v[62:63], v[140:141]
	v_mov_b64_e32 v[64:65], v[142:143]
	v_mov_b64_e32 v[66:67], v[144:145]
	v_sqrt_f32_e32 v77, v76
	v_pk_mul_f32 v[22:23], v[22:23], v[80:81]
	v_pk_mul_f32 v[12:13], v[12:13], v[20:21]
	v_add_u32_e32 v0, -1, v77
	v_fma_f32 v82, -v0, v77, v76
	v_cmp_ge_f32_e64 s[0:1], 0, v82
	v_add_u32_e32 v82, 1, v77
	s_nop 0
	v_cndmask_b32_e64 v0, v77, v0, s[0:1]
	v_fma_f32 v77, -v82, v77, v76
	v_cmp_lt_f32_e64 s[0:1], 0, v77
	s_nop 1
	v_cndmask_b32_e64 v0, v0, v82, s[0:1]
	v_mul_f32_e32 v77, 0x37800000, v0
	v_cndmask_b32_e32 v0, v0, v77, vcc
	v_cmp_class_f32_e32 vcc, v76, v212
	s_nop 1
	v_cndmask_b32_e32 v0, v0, v76, vcc
	v_div_scale_f32 v76, s[0:1], v0, v0, 1.0
	v_rcp_f32_e32 v77, v76
	s_nop 0
	v_fma_f32 v18, -v76, v77, 1.0
	v_fmac_f32_e32 v77, v18, v77
	v_div_scale_f32 v18, vcc, 1.0, v0, 1.0
	v_mul_f32_e32 v19, v18, v77
	v_fma_f32 v78, -v76, v19, v18
	v_fmac_f32_e32 v19, v78, v77
	v_fma_f32 v18, -v76, v19, v18
	v_div_fmas_f32 v18, v18, v77, v19
	v_div_fixup_f32 v0, v18, v0, 1.0
	v_mul_f32_e32 v0, 0x3e38aa3b, v0
	v_pk_mul_f32 v[18:19], v[0:1], v[88:89] op_sel_hi:[0,1]
	v_pk_mul_f32 v[18:19], v[30:31], v[18:19]
	s_nop 0
	v_cvt_pk_bf16_f32 v162, v18, v19
	v_pk_mul_f32 v[18:19], v[0:1], v[70:71] op_sel_hi:[0,1]
	v_pk_mul_f32 v[18:19], v[28:29], v[18:19]
	s_nop 0
	v_cvt_pk_bf16_f32 v163, v18, v19
	v_pk_mul_f32 v[18:19], v[0:1], v[86:87] op_sel_hi:[0,1]
	v_pk_mul_f32 v[18:19], v[26:27], v[18:19]
	s_nop 0
	v_cvt_pk_bf16_f32 v164, v18, v19
	v_pk_mul_f32 v[18:19], v[0:1], v[84:85] op_sel_hi:[0,1]
	v_pk_mul_f32 v[18:19], v[34:35], v[18:19]
	s_nop 0
	v_cvt_pk_bf16_f32 v165, v18, v19
	v_pk_mul_f32 v[18:19], v[0:1], v[92:93] op_sel_hi:[0,1]
	v_pk_mul_f32 v[18:19], v[22:23], v[18:19]
	ds_write_b128 v207, v[162:165]
	v_cvt_pk_bf16_f32 v166, v18, v19
	v_pk_mul_f32 v[18:19], v[0:1], v[74:75] op_sel_hi:[0,1]
	v_pk_mul_f32 v[18:19], v[18:19], v[24:25]
	s_nop 0
	v_cvt_pk_bf16_f32 v167, v18, v19
	v_pk_mul_f32 v[18:19], v[0:1], v[90:91] op_sel_hi:[0,1]
	v_pk_mul_f32 v[18:19], v[18:19], v[14:15]
	s_nop 0
	v_cvt_pk_bf16_f32 v168, v18, v19
	v_pk_mul_f32 v[18:19], v[0:1], v[68:69] op_sel_hi:[0,1]
	v_pk_mul_f32 v[18:19], v[18:19], v[16:17]
	v_pk_mul_f32 v[68:69], v[2:3], v[6:7]
	v_cvt_pk_bf16_f32 v169, v18, v19
	v_pk_mul_f32 v[18:19], v[0:1], v[94:95] op_sel_hi:[0,1]
	v_pk_mul_f32 v[18:19], v[18:19], v[10:11]
	ds_write_b128 v207, v[166:169] offset:1024
	v_cvt_pk_bf16_f32 v170, v18, v19
	v_pk_mul_f32 v[18:19], v[0:1], v[72:73] op_sel_hi:[0,1]
	v_pk_mul_f32 v[18:19], v[18:19], v[12:13]
	s_nop 0
	v_cvt_pk_bf16_f32 v171, v18, v19
	v_mov_b32_e32 v18, v44
	v_mov_b32_e32 v19, v46
	v_pk_mul_f32 v[18:19], v[0:1], v[18:19] op_sel_hi:[0,1]
	v_pk_mul_f32 v[2:3], v[18:19], v[68:69]
	v_mov_b32_e32 v46, v45
	v_cvt_pk_bf16_f32 v172, v2, v3
	v_pk_mul_f32 v[2:3], v[0:1], v[46:47] op_sel_hi:[0,1]
	v_pk_mul_f32 v[44:45], v[4:5], v[8:9]
	s_waitcnt vmcnt(0)
	v_pk_mul_f32 v[46:47], v[56:57], v[64:65]
	v_pk_mul_f32 v[2:3], v[2:3], v[44:45]
	s_nop 0
	v_cvt_pk_bf16_f32 v173, v2, v3
	v_mov_b32_e32 v2, v42
	v_mov_b32_e32 v3, v40
	v_pk_mul_f32 v[2:3], v[0:1], v[2:3] op_sel_hi:[0,1]
	v_pk_mul_f32 v[2:3], v[2:3], v[46:47]
	v_mov_b32_e32 v40, v43
	v_cvt_pk_bf16_f32 v174, v2, v3
	v_pk_mul_f32 v[2:3], v[0:1], v[40:41] op_sel_hi:[0,1]
	v_pk_mul_f32 v[40:41], v[58:59], v[66:67]
	v_pk_mul_f32 v[42:43], v[52:53], v[60:61]
	v_pk_mul_f32 v[2:3], v[2:3], v[40:41]
	v_pk_mul_f32 v[52:53], v[54:55], v[62:63]
	v_cvt_pk_bf16_f32 v175, v2, v3
	v_mov_b32_e32 v2, v38
	v_mov_b32_e32 v3, v36
	v_pk_mul_f32 v[2:3], v[0:1], v[2:3] op_sel_hi:[0,1]
	v_pk_mul_f32 v[2:3], v[2:3], v[42:43]
	v_mov_b32_e32 v36, v39
	v_cvt_pk_bf16_f32 v176, v2, v3
	v_pk_mul_f32 v[2:3], v[0:1], v[36:37] op_sel_hi:[0,1]
	v_pk_mul_f32 v[2:3], v[2:3], v[52:53]
	ds_write_b128 v207, v[170:173] offset:2048
	v_cvt_pk_bf16_f32 v177, v2, v3
	ds_write_b128 v207, v[174:177] offset:3072
	v_mov_b64_e32 v[2:3], v[146:147]
	v_mov_b64_e32 v[4:5], v[148:149]
	v_mov_b64_e32 v[6:7], v[150:151]
	v_mov_b64_e32 v[8:9], v[152:153]
	v_mov_b64_e32 v[18:19], v[154:155]
	v_mov_b64_e32 v[20:21], v[156:157]
	v_mov_b64_e32 v[36:37], v[158:159]
	v_mov_b64_e32 v[38:39], v[160:161]
	s_waitcnt vmcnt(0) lgkmcnt(0)
; #define LAS __attribute__((address_space(3)))
; __device__ __forceinline__ unsigned pk2(float lo, float hi) { f32x2 v = {lo, hi}; bf16x2_t b = __builtin_convertvector(v, bf16x2_t); return __builtin_bit_cast(unsigned, b); }
; __device__ __forceinline__ float bflo(unsigned u) { return __uint_as_float(u << 16); }
; __device__ __forceinline__ float bfhi(unsigned u) { return __uint_as_float(u & 0xffff0000u); }
; template <int MODE>
; __device__ __forceinline__ void attn_item(const AttnP& p, int b, int h, int qb, LAS unsigned char* lds) {
;     ...
;         u32x4 raw[4]; float ss = 0.f;
; #pragma unroll
;         for (int ks = 0; ks < 4; ++ks) {
;             raw[ks] = *(const u32x4*)(P + (size_t)(tok0 + qrow) * PP + qcol + c * 64 + ks * 16 + hh * 8);
; #pragma unroll
;             for (int e = 0; e < 4; ++e) { const float lo = bflo(raw[ks][e]), hi = bfhi(raw[ks][e]); ss += lo * lo + hi * hi; }
;         }
;         float sc = 0.125f * LOG2E;
;         if (MODE != 1) { ss += __shfl_xor(ss, 32); sc *= 1.0f / sqrtf(ss * (1.0f / 64.0f) + 1e-6f); }
; #pragma unroll
;         for (int ks = 0; ks < 4; ++ks) {
;             u32x4 o;
; #pragma unroll
;             for (int e = 0; e < 4; ++e) {
;                 float lo = bflo(raw[ks][e]) * sc, hi = bfhi(raw[ks][e]) * sc;
;                 if (MODE != 1) {
;                     const int d = ks * 16 + hh * 8 + 2 * e;
;                     const float* gq = p.qk_gain + ((MODE == 0) ? 0 : 128); const float* gk = gq + 64;
;                     lo *= gq[d] * gk[d]; hi *= gq[d + 1] * gk[d + 1];
;                 }
;                 o[e] = pk2(lo, hi);
;             }
;             Qf[c][ks] = __builtin_bit_cast(bf16x8, o);
;             if (QPARK) *(LAS u32x4*)(lds + QP_OFF + w * 8192 + ((c * 4 + ks) * 64 + lane) * 16) = o;
;         }
;     }
;     if (MODE == 0) { LAS float* tab = (LAS float*)(lds + TAB_OFF); if (tid < 256) tab[tid] = p.biasT[h * 256 + tid]; }
	v_lshlrev_b32_e32 v94, 16, v2
	v_and_b32_e32 v95, 0xffff0000, v2
	v_lshlrev_b32_e32 v64, 16, v21
	v_and_b32_e32 v65, 0xffff0000, v21
	v_lshlrev_b32_e32 v72, 16, v19
	v_and_b32_e32 v73, 0xffff0000, v19
	v_lshlrev_b32_e32 v76, 16, v18
	v_and_b32_e32 v77, 0xffff0000, v18
	v_pk_mul_f32 v[66:67], v[64:65], v[64:65]
	v_lshlrev_b32_e32 v70, 16, v20
	v_and_b32_e32 v71, 0xffff0000, v20
	v_pk_mul_f32 v[74:75], v[72:73], v[72:73]
	v_pk_mul_f32 v[18:19], v[76:77], v[76:77]
	v_pk_mul_f32 v[20:21], v[70:71], v[70:71]
	v_add_f32_e32 v0, v66, v67
	v_add_f32_e32 v66, v74, v75
	v_add_f32_e32 v18, v18, v19
	v_lshlrev_b32_e32 v88, 16, v36
	v_and_b32_e32 v89, 0xffff0000, v36
	v_add_f32_e32 v18, v18, v66
	v_add_f32_e32 v19, v20, v21
	v_lshlrev_b32_e32 v84, 16, v37
	v_and_b32_e32 v85, 0xffff0000, v37
	v_pk_mul_f32 v[36:37], v[88:89], v[88:89]
	v_add_f32_e32 v18, v19, v18
	v_lshlrev_b32_e32 v82, 16, v38
	v_and_b32_e32 v83, 0xffff0000, v38
	v_pk_mul_f32 v[86:87], v[84:85], v[84:85]
	v_add_f32_e32 v0, v0, v18
	v_add_f32_e32 v18, v36, v37
	v_lshlrev_b32_e32 v78, 16, v39
	v_and_b32_e32 v79, 0xffff0000, v39
	v_pk_mul_f32 v[38:39], v[82:83], v[82:83]
	v_add_f32_e32 v0, v18, v0
	v_add_f32_e32 v18, v86, v87
	v_pk_mul_f32 v[80:81], v[78:79], v[78:79]
	v_add_f32_e32 v0, v18, v0
	v_add_f32_e32 v18, v38, v39
	v_lshlrev_b32_e32 v90, 16, v3
	v_and_b32_e32 v91, 0xffff0000, v3
	v_pk_mul_f32 v[2:3], v[94:95], v[94:95]
	v_add_f32_e32 v0, v18, v0
	v_add_f32_e32 v18, v80, v81
	v_and_b32_e32 v55, 0xffff0000, v5
	v_and_b32_e32 v54, 0xffff0000, v4
	v_pk_mul_f32 v[92:93], v[90:91], v[90:91]
	v_add_f32_e32 v0, v18, v0
	v_add_f32_e32 v2, v2, v3
	v_lshlrev_b32_e32 v33, 16, v5
	v_lshlrev_b32_e32 v32, 16, v4
	v_pk_mul_f32 v[4:5], v[54:55], v[54:55]
	v_add_f32_e32 v0, v2, v0
	v_add_f32_e32 v2, v92, v93
	v_pk_fma_f32 v[4:5], v[32:33], v[32:33], v[4:5]
	v_lshlrev_b32_e32 v57, 16, v7
	v_lshlrev_b32_e32 v56, 16, v6
	v_and_b32_e32 v7, 0xffff0000, v7
	v_and_b32_e32 v6, 0xffff0000, v6
	v_add_f32_e32 v0, v2, v0
	v_pk_mul_f32 v[58:59], v[6:7], v[6:7]
	v_add_f32_e32 v0, v4, v0
	v_pk_fma_f32 v[58:59], v[56:57], v[56:57], v[58:59]
	v_lshlrev_b32_e32 v61, 16, v9
	v_lshlrev_b32_e32 v60, 16, v8
	v_and_b32_e32 v9, 0xffff0000, v9
	v_and_b32_e32 v8, 0xffff0000, v8
	v_add_f32_e32 v0, v5, v0
	v_pk_mul_f32 v[62:63], v[8:9], v[8:9]
	v_add_f32_e32 v0, v58, v0
	v_pk_fma_f32 v[62:63], v[60:61], v[60:61], v[62:63]
	v_add_f32_e32 v0, v59, v0
	v_add_f32_e32 v0, v62, v0
	v_add_f32_e32 v0, v63, v0
	ds_bpermute_b32 v2, v226, v0
	s_waitcnt lgkmcnt(0)
	v_add_f32_e32 v0, v0, v2
	v_fmamk_f32 v0, v0, 0x3c800000, v211
	v_mul_f32_e32 v2, 0x4f800000, v0
	v_cmp_gt_f32_e32 vcc, s7, v0
	s_nop 1
	v_cndmask_b32_e32 v0, v0, v2, vcc
	v_sqrt_f32_e32 v2, v0
	s_nop 0
	v_add_u32_e32 v3, -1, v2
	v_fma_f32 v4, -v3, v2, v0
	v_cmp_ge_f32_e64 s[0:1], 0, v4
	v_add_u32_e32 v4, 1, v2
	s_nop 0
	v_cndmask_b32_e64 v3, v2, v3, s[0:1]
	v_fma_f32 v2, -v4, v2, v0
	v_cmp_lt_f32_e64 s[0:1], 0, v2
	s_nop 1
	v_cndmask_b32_e64 v2, v3, v4, s[0:1]
	v_mul_f32_e32 v3, 0x37800000, v2
	v_cndmask_b32_e32 v2, v2, v3, vcc
	v_cmp_class_f32_e32 vcc, v0, v212
	s_nop 1
	v_cndmask_b32_e32 v0, v2, v0, vcc
	v_div_scale_f32 v2, s[0:1], v0, v0, 1.0
	v_rcp_f32_e32 v3, v2
	s_movk_i32 s0, 0x100
	v_fma_f32 v4, -v2, v3, 1.0
	v_fmac_f32_e32 v3, v4, v3
	v_div_scale_f32 v4, vcc, 1.0, v0, 1.0
	v_mul_f32_e32 v5, v4, v3
	v_fma_f32 v18, -v2, v5, v4
	v_fmac_f32_e32 v5, v18, v3
	v_fma_f32 v2, -v2, v5, v4
	v_div_fmas_f32 v2, v2, v3, v5
	v_div_fixup_f32 v0, v2, v0, 1.0
	v_mul_f32_e32 v0, 0x3e38aa3b, v0
	v_pk_mul_f32 v[2:3], v[0:1], v[76:77] op_sel_hi:[0,1]
	v_pk_mul_f32 v[4:5], v[0:1], v[72:73] op_sel_hi:[0,1]
	v_pk_mul_f32 v[2:3], v[30:31], v[2:3]
	v_pk_mul_f32 v[4:5], v[28:29], v[4:5]
	v_cvt_pk_bf16_f32 v2, v2, v3
	v_cvt_pk_bf16_f32 v3, v4, v5
	v_pk_mul_f32 v[4:5], v[0:1], v[70:71] op_sel_hi:[0,1]
	v_pk_mul_f32 v[18:19], v[0:1], v[64:65] op_sel_hi:[0,1]
	v_pk_mul_f32 v[4:5], v[26:27], v[4:5]
	v_pk_mul_f32 v[18:19], v[34:35], v[18:19]
	v_cvt_pk_bf16_f32 v4, v4, v5
	v_cvt_pk_bf16_f32 v5, v18, v19
	ds_write_b128 v207, v[2:5] offset:4096
	v_pk_mul_f32 v[2:3], v[0:1], v[88:89] op_sel_hi:[0,1]
	v_pk_mul_f32 v[4:5], v[0:1], v[84:85] op_sel_hi:[0,1]
	v_pk_mul_f32 v[2:3], v[22:23], v[2:3]
	v_pk_mul_f32 v[4:5], v[24:25], v[4:5]
	v_cvt_pk_bf16_f32 v2, v2, v3
	v_cvt_pk_bf16_f32 v3, v4, v5
	v_pk_mul_f32 v[4:5], v[0:1], v[82:83] op_sel_hi:[0,1]
	v_pk_mul_f32 v[4:5], v[14:15], v[4:5]
	v_pk_mul_f32 v[14:15], v[0:1], v[78:79] op_sel_hi:[0,1]
	v_pk_mul_f32 v[14:15], v[16:17], v[14:15]
	v_cvt_pk_bf16_f32 v4, v4, v5
	v_cvt_pk_bf16_f32 v5, v14, v15
	ds_write_b128 v207, v[2:5] offset:5120
	v_pk_mul_f32 v[2:3], v[0:1], v[94:95] op_sel_hi:[0,1]
	v_pk_mul_f32 v[4:5], v[0:1], v[90:91] op_sel_hi:[0,1]
	v_pk_mul_f32 v[2:3], v[10:11], v[2:3]
	v_pk_mul_f32 v[4:5], v[12:13], v[4:5]
	v_cvt_pk_bf16_f32 v2, v2, v3
	v_cvt_pk_bf16_f32 v3, v4, v5
	v_mov_b32_e32 v4, v32
	v_mov_b32_e32 v5, v54
	v_mov_b32_e32 v54, v33
	v_pk_mul_f32 v[4:5], v[0:1], v[4:5] op_sel_hi:[0,1]
	v_pk_mul_f32 v[10:11], v[0:1], v[54:55] op_sel_hi:[0,1]
	v_pk_mul_f32 v[4:5], v[68:69], v[4:5]
	v_pk_mul_f32 v[10:11], v[44:45], v[10:11]
	v_cvt_pk_bf16_f32 v4, v4, v5
	v_cvt_pk_bf16_f32 v5, v10, v11
	ds_write_b128 v207, v[2:5] offset:6144
	v_mov_b32_e32 v2, v56
	v_mov_b32_e32 v3, v6
	v_mov_b32_e32 v6, v57
	v_pk_mul_f32 v[2:3], v[0:1], v[2:3] op_sel_hi:[0,1]
	v_pk_mul_f32 v[4:5], v[0:1], v[6:7] op_sel_hi:[0,1]
	v_pk_mul_f32 v[2:3], v[46:47], v[2:3]
	v_pk_mul_f32 v[4:5], v[40:41], v[4:5]
	v_cvt_pk_bf16_f32 v2, v2, v3
	v_cvt_pk_bf16_f32 v3, v4, v5
	v_mov_b32_e32 v4, v60
	v_mov_b32_e32 v5, v8
	v_mov_b32_e32 v8, v61
	v_pk_mul_f32 v[4:5], v[0:1], v[4:5] op_sel_hi:[0,1]
	v_pk_mul_f32 v[6:7], v[0:1], v[8:9] op_sel_hi:[0,1]
	v_pk_mul_f32 v[4:5], v[42:43], v[4:5]
	v_pk_mul_f32 v[6:7], v[52:53], v[6:7]
	v_cvt_pk_bf16_f32 v4, v4, v5
	v_cvt_pk_bf16_f32 v5, v6, v7
	v_cmp_gt_i32_e32 vcc, s0, v50
	ds_write_b128 v207, v[2:5] offset:7168
	s_and_saveexec_b64 s[0:1], vcc
	s_cbranch_execz .LBB0_494
	v_lshl_add_u32 v2, s6, 8, v50
	v_ashrrev_i32_e32 v3, 31, v2
	v_lshl_add_u64 v[2:3], v[2:3], 2, s[42:43]
	v_mov_b32_e32 v0, v194
	v_lshl_add_u32 v2, v50, 2, 0
	v_add_u32_e32 v2, 0x12a00, v2
	s_waitcnt vmcnt(0) lgkmcnt(0)
	ds_write_b32 v2, v0
; #define ATT_LOAD(jt) do { ATT_LOADK(jt); ATT_LOADV(jt); } while (0)
; template <int MODE>
; __device__ __forceinline__ void attn_item(const AttnP& p, int b, int h, int qb, LAS unsigned char* lds) {
;     ...
;     ATT_LOAD(jt_max);
;     ATT_STORE(0, jt_max);
;     __syncthreads();
.LBB0_494:
	s_or_b64 exec, exec, s[0:1]
	s_lshl_b32 s0, s5, 2
	v_ashrrev_i32_e32 v4, 3, v50
	s_or_b32 s10, s0, 3
	v_add_u32_e32 v229, s8, v4
	v_lshl_add_u32 v0, s10, 6, v229
	v_mov_b64_e32 v[2:3], s[46:47]
	v_mad_i64_i32 v[2:3], s[0:1], v0, s76, v[2:3]
	v_lshlrev_b32_e32 v0, 3, v50
	v_and_b32_e32 v34, 56, v0
	s_lshl_b32 s0, s9, 1
	s_mov_b32 s1, s93
	v_lshl_add_u64 v[2:3], v[2:3], 0, s[0:1]
	v_lshlrev_b32_e32 v0, 1, v34
	v_lshl_add_u64 v[2:3], v[2:3], 0, v[0:1]
	v_mul_lo_u32 v35, v4, 24
	s_movk_i32 s1, 0x88
	v_mad_u64_u32 v[4:5], s[6:7], v4, s1, v[34:35]
	v_lshlrev_b32_e32 v231, 1, v4
	v_add_lshl_u32 v232, v4, v35, 1
	v_add_u32_e32 v36, 64, v4
	v_add_lshl_u32 v234, v36, v35, 1
	v_add_u32_e32 v37, 0, v231
	v_lshlrev_b32_e32 v233, 1, v36
	v_add_u32_e32 v38, 0, v232
	v_add_u32_e32 v39, 0, v233
	v_lshlrev_b32_e32 v230, 2, v48
	v_and_b32_e32 v41, 16, v50
	s_or_b32 s5, s9, 0x200
	s_or_b32 s6, s9, 0x400
	s_or_b32 s1, s4, 31
	v_mul_u32_u24_e32 v235, 0x110, v49
	s_lshl_b32 s4, s2, 2
	v_mad_i32_i24 v236, v48, -4, v49
	s_lshl_b32 s2, s2, 8
	s_add_i32 s11, s3, 0xffffff01
	v_mov_b32_e32 v208, v1
	v_mov_b32_e32 v209, v1
	s_mov_b32 s12, 0
	s_sub_i32 s13, 64, s4
	s_sub_i32 s14, 0xf80, s2
	s_lshl_b32 s92, s5, 1
	s_lshl_b32 s4, s6, 1
	s_waitcnt vmcnt(0) lgkmcnt(0)
	v_and_b32_e32 v3, 0xffff0000, v181
	v_and_b32_e32 v5, 0xffff0000, v180
	v_and_b32_e32 v7, 0xffff0000, v179
	v_and_b32_e32 v9, 0xffff0000, v178
	v_lshlrev_b32_e32 v2, 16, v181
	v_lshlrev_b32_e32 v4, 16, v180
	v_lshlrev_b32_e32 v6, 16, v179
	v_lshlrev_b32_e32 v8, 16, v178
	v_and_b32_e32 v15, 0xffff0000, v183
	v_and_b32_e32 v17, 0xffff0000, v182
	v_mov_b32_e32 v20, v3
	v_mov_b32_e32 v21, v5
	v_mov_b32_e32 v24, v9
	v_mov_b32_e32 v25, v7
	v_and_b32_e32 v11, 0xffff0000, v185
	v_and_b32_e32 v13, 0xffff0000, v184
	v_lshlrev_b32_e32 v14, 16, v183
	v_lshlrev_b32_e32 v16, 16, v182
	v_mov_b32_e32 v18, v2
	v_mov_b32_e32 v19, v4
	v_mov_b32_e32 v22, v8
	v_mov_b32_e32 v23, v6
	v_mov_b32_e32 v32, v17
	v_mov_b32_e32 v33, v15
	v_pk_mul_f32 v[20:21], v[20:21], v[20:21]
	v_pk_mul_f32 v[24:25], v[24:25], v[24:25]
	v_lshlrev_b32_e32 v10, 16, v185
	v_lshlrev_b32_e32 v12, 16, v184
	v_mov_b32_e32 v28, v11
	v_mov_b32_e32 v29, v13
	v_mov_b32_e32 v30, v16
	v_mov_b32_e32 v31, v14
	v_pk_mul_f32 v[32:33], v[32:33], v[32:33]
	v_pk_fma_f32 v[18:19], v[18:19], v[18:19], v[20:21]
	v_pk_fma_f32 v[20:21], v[22:23], v[22:23], v[24:25]
	v_mov_b32_e32 v26, v10
	v_mov_b32_e32 v27, v12
	v_pk_mul_f32 v[28:29], v[28:29], v[28:29]
	v_pk_fma_f32 v[24:25], v[30:31], v[30:31], v[32:33]
	v_add_f32_e32 v0, v20, v21
	v_pk_fma_f32 v[22:23], v[26:27], v[26:27], v[28:29]
	v_add_f32_e32 v20, v24, v25
	v_add_f32_e32 v0, v19, v0
	v_add_f32_e32 v19, v23, v20
	v_add_f32_e32 v0, v18, v0
	v_add_f32_e32 v18, v22, v19
	s_nop 0
	v_add_f32_dpp v0, v0, v0 quad_perm:[1,0,3,2] row_mask:0xf bank_mask:0xf bound_ctrl:1
	v_add_f32_dpp v18, v18, v18 quad_perm:[1,0,3,2] row_mask:0xf bank_mask:0xf bound_ctrl:1
	s_nop 0
	v_add_f32_dpp v0, v0, v0 quad_perm:[2,3,0,1] row_mask:0xf bank_mask:0xf bound_ctrl:1
	v_add_f32_dpp v18, v18, v18 quad_perm:[2,3,0,1] row_mask:0xf bank_mask:0xf bound_ctrl:1
	s_nop 0
	v_add_f32_dpp v0, v0, v0 row_half_mirror row_mask:0xf bank_mask:0xf bound_ctrl:1
	v_fmamk_f32 v0, v0, 0x3c800000, v211
	v_add_f32_dpp v18, v18, v18 row_half_mirror row_mask:0xf bank_mask:0xf bound_ctrl:1
	v_rsq_f32_e32 v0, v0
	v_fmamk_f32 v18, v18, 0x3c800000, v211
	v_rsq_f32_e32 v18, v18
	v_pk_mul_f32 v[8:9], v[0:1], v[8:9] op_sel_hi:[0,1]
	v_pk_mul_f32 v[6:7], v[0:1], v[6:7] op_sel_hi:[0,1]
	v_pk_mul_f32 v[4:5], v[0:1], v[4:5] op_sel_hi:[0,1]
	v_pk_mul_f32 v[20:21], v[0:1], v[2:3] op_sel_hi:[0,1]
	v_pk_mul_f32 v[16:17], v[18:19], v[16:17] op_sel_hi:[0,1]
	v_pk_mul_f32 v[14:15], v[18:19], v[14:15] op_sel_hi:[0,1]
	v_pk_mul_f32 v[12:13], v[18:19], v[12:13] op_sel_hi:[0,1]
	v_pk_mul_f32 v[10:11], v[18:19], v[10:11] op_sel_hi:[0,1]
	v_cvt_pk_bf16_f32 v2, v8, v9
	v_cvt_pk_bf16_f32 v3, v6, v7
	v_cvt_pk_bf16_f32 v4, v4, v5
	v_cvt_pk_bf16_f32 v5, v20, v21
	v_add_u32_e32 v0, 0, v234
	v_cvt_pk_bf16_f32 v6, v16, v17
	v_cvt_pk_bf16_f32 v7, v14, v15
	v_cvt_pk_bf16_f32 v8, v12, v13
	v_cvt_pk_bf16_f32 v9, v10, v11
	ds_write_b128 v37, v[2:5]
	ds_write_b128 v38, v[186:189] offset:17408
	ds_write_b128 v39, v[6:9]
	ds_write_b128 v0, v[190:193] offset:17408
	v_lshlrev_b32_e32 v0, 2, v51
	s_waitcnt lgkmcnt(0)
	s_barrier
; #define LAS __attribute__((address_space(3)))
; template <int MODE>
; __device__ __forceinline__ void attn_item(const AttnP& p, int b, int h, int qb, LAS unsigned char* lds) {
;     ...
;     f32x16 O[NC][DV / 32];
; #pragma unroll
;     for (int c = 0; c < NC; ++c)
; #pragma unroll
;         for (int d = 0; d < DV / 32; ++d)
; #pragma unroll
;             for (int i = 0; i < 16; ++i) O[c][d][i] = 0.f;
;     float mrun[NC], lsum[NC];
; #pragma unroll
;     for (int c = 0; c < NC; ++c) { mrun[c] = -1e30f; lsum[c] = 0.f; }
;     ...
;     float mfix = 0.f;
;     if (MODE == 2) mfix = qk2;
;     if (MODE == 0) {
;         float gq_ = fabsf(p.qk_gain[lane]), gk_ = fabsf(p.qk_gain[64 + lane]);
;         const LAS float* tab_ = (const LAS float*)(lds + TAB_OFF);
;         float tm_ = fmaxf(fmaxf(fabsf(tab_[lane]), fabsf(tab_[64 + lane])), fmaxf(fabsf(tab_[128 + lane]), fabsf(tab_[192 + lane])));
; #pragma unroll
;         for (int o_ = 1; o_ < 64; o_ <<= 1) { gq_ = fmaxf(gq_, __shfl_xor(gq_, o_)); gk_ = fmaxf(gk_, __shfl_xor(gk_, o_)); tm_ = fmaxf(tm_, __shfl_xor(tm_, o_)); }
;         mfix = 8.0f * gq_ * gk_ * LOG2E * 1.02f + tm_;
;     }
	v_mov_b32_e32 v35, v195
	v_mov_b32_e32 v40, v204
	v_add_u32_e32 v0, 0, v0
	v_add_u32_e32 v0, 0x12a00, v0
	ds_read2st64_b32 v[36:37], v0 offset1:1
	ds_read2st64_b32 v[38:39], v0 offset0:2 offset1:3
	v_lshrrev_b32_e32 v18, 2, v50
	v_lshlrev_b32_e32 v19, 2, v50
	v_and_or_b32 v42, v18, 3, v230
	v_and_b32_e32 v43, 12, v19
	s_waitcnt lgkmcnt(0)
	v_max_f32_e64 v39, |v39|, |v39|
	v_max_f32_e64 v38, |v38|, |v38|
	v_max_f32_e32 v38, v38, v39
	v_max3_f32 v36, |v36|, |v37|, v38
	ds_bpermute_b32 v37, v221, v36
	v_mul_u32_u24_e32 v0, 0xa0, v42
	v_or3_b32 v0, v43, v41, v0
	v_lshlrev_b32_e32 v237, 1, v0
	v_mov_b32_e32 v16, v1
	s_waitcnt lgkmcnt(0)
	v_max_f32_e32 v0, v37, v37
	v_max_f32_e32 v0, v36, v0
	ds_bpermute_b32 v38, v222, v0
	v_mov_b32_e32 v17, v1
	v_mov_b32_e32 v2, v1
	v_mov_b32_e32 v3, v1
	v_mov_b32_e32 v4, v1
	s_waitcnt lgkmcnt(0)
	v_max_f32_e32 v38, v38, v38
	v_max_f32_e32 v0, v0, v38
	ds_bpermute_b32 v38, v223, v0
	v_mov_b32_e32 v5, v1
	v_mov_b32_e32 v6, v1
	v_mov_b32_e32 v7, v1
	v_mov_b32_e32 v8, v1
	s_waitcnt lgkmcnt(0)
	v_max_f32_e32 v38, v38, v38
	v_max_f32_e32 v0, v0, v38
	ds_bpermute_b32 v38, v224, v0
	v_mov_b32_e32 v9, v1
	v_mov_b32_e32 v10, v1
	v_mov_b32_e32 v11, v1
	v_mov_b32_e32 v12, v1
	s_waitcnt lgkmcnt(0)
	v_max_f32_e32 v38, v38, v38
	v_max_f32_e32 v0, v0, v38
	ds_bpermute_b32 v38, v225, v0
	v_mov_b32_e32 v13, v1
	v_mov_b32_e32 v14, v1
	v_mov_b32_e32 v15, v1
	v_mov_b64_e32 v[32:33], v[16:17]
	s_waitcnt lgkmcnt(0)
	v_max_f32_e32 v38, v38, v38
	v_max_f32_e32 v38, v0, v38
	v_mov_b64_e32 v[80:81], v[16:17]
	v_mov_b64_e32 v[112:113], v[16:17]
	v_mov_b64_e32 v[64:65], v[16:17]
	v_mov_b64_e32 v[96:97], v[16:17]
	v_mov_b64_e32 v[128:129], v[16:17]
	v_mov_b64_e32 v[30:31], v[14:15]
	v_mov_b64_e32 v[28:29], v[12:13]
	v_mov_b64_e32 v[26:27], v[10:11]
	v_mov_b64_e32 v[24:25], v[8:9]
	v_mov_b64_e32 v[22:23], v[6:7]
	v_mov_b64_e32 v[20:21], v[4:5]
	v_mov_b64_e32 v[18:19], v[2:3]
	v_mov_b64_e32 v[78:79], v[14:15]
	v_mov_b64_e32 v[76:77], v[12:13]
	v_mov_b64_e32 v[74:75], v[10:11]
	v_mov_b64_e32 v[72:73], v[8:9]
	v_mov_b64_e32 v[70:71], v[6:7]
	v_mov_b64_e32 v[68:69], v[4:5]
	v_mov_b64_e32 v[66:67], v[2:3]
	v_mov_b64_e32 v[110:111], v[14:15]
	v_mov_b64_e32 v[108:109], v[12:13]
	v_mov_b64_e32 v[106:107], v[10:11]
	v_mov_b64_e32 v[104:105], v[8:9]
	v_mov_b64_e32 v[102:103], v[6:7]
	v_mov_b64_e32 v[100:101], v[4:5]
	v_mov_b64_e32 v[98:99], v[2:3]
	v_add_u32_e32 v238, 0x2800, v237
	v_add_u32_e32 v239, 0x3c00, v237
	v_add_u32_e32 v240, 0x1400, v237
	v_mov_b64_e32 v[62:63], v[14:15]
	v_mov_b64_e32 v[60:61], v[12:13]
	v_mov_b64_e32 v[58:59], v[10:11]
	s_waitcnt vmcnt(1)
	v_and_b32_e32 v36, 0x7fffffff, v35
	s_waitcnt vmcnt(0)
	v_and_b32_e32 v37, 0x7fffffff, v40
	ds_bpermute_b32 v36, v221, v36
	ds_bpermute_b32 v37, v221, v37
	v_max_f32_e64 v35, |v35|, |v35|
	v_max_f32_e64 v39, |v40|, |v40|
	ds_bpermute_b32 v40, v226, v38
	s_waitcnt lgkmcnt(2)
	v_max_f32_e32 v36, v36, v36
	s_waitcnt lgkmcnt(1)
	v_max_f32_e32 v37, v37, v37
	v_max_f32_e32 v35, v35, v36
	v_max_f32_e32 v36, v39, v37
	ds_bpermute_b32 v37, v222, v35
	ds_bpermute_b32 v39, v222, v36
	v_mov_b64_e32 v[56:57], v[8:9]
	v_mov_b64_e32 v[54:55], v[6:7]
	v_mov_b64_e32 v[52:53], v[4:5]
	s_waitcnt lgkmcnt(1)
	v_max_f32_e32 v37, v37, v37
	s_waitcnt lgkmcnt(0)
	v_max_f32_e32 v39, v39, v39
	v_max_f32_e32 v35, v35, v37
	v_max_f32_e32 v36, v36, v39
	ds_bpermute_b32 v37, v223, v35
	ds_bpermute_b32 v39, v223, v36
	v_mov_b64_e32 v[50:51], v[2:3]
	v_mov_b64_e32 v[94:95], v[14:15]
	v_mov_b64_e32 v[92:93], v[12:13]
	s_waitcnt lgkmcnt(1)
	v_max_f32_e32 v37, v37, v37
	s_waitcnt lgkmcnt(0)
	v_max_f32_e32 v39, v39, v39
	v_max_f32_e32 v35, v35, v37
	v_max_f32_e32 v36, v36, v39
	ds_bpermute_b32 v37, v224, v35
	ds_bpermute_b32 v39, v224, v36
	v_mov_b64_e32 v[90:91], v[10:11]
	v_mov_b64_e32 v[88:89], v[8:9]
	v_mov_b64_e32 v[86:87], v[6:7]
	s_waitcnt lgkmcnt(1)
	v_max_f32_e32 v37, v37, v37
	s_waitcnt lgkmcnt(0)
	v_max_f32_e32 v39, v39, v39
	v_max_f32_e32 v35, v35, v37
	v_max_f32_e32 v36, v36, v39
	ds_bpermute_b32 v37, v225, v35
	ds_bpermute_b32 v39, v225, v36
	v_mov_b64_e32 v[84:85], v[4:5]
	v_mov_b64_e32 v[82:83], v[2:3]
	v_mov_b64_e32 v[126:127], v[14:15]
	s_waitcnt lgkmcnt(1)
	v_max_f32_e32 v0, v37, v37
	s_waitcnt lgkmcnt(0)
	v_max_f32_e32 v37, v39, v39
	v_max_f32_e32 v35, v35, v0
	v_max_f32_e32 v36, v36, v37
	ds_bpermute_b32 v37, v226, v35
	ds_bpermute_b32 v39, v226, v36
	v_lshlrev_b32_e32 v0, 1, v34
	v_max_f32_e32 v34, v40, v40
	v_max_f32_e32 v241, v38, v34
	s_waitcnt lgkmcnt(1)
	v_max_f32_e32 v34, v37, v37
	s_waitcnt lgkmcnt(0)
	v_max_f32_e32 v37, v39, v39
	v_max_f32_e32 v34, v35, v34
	v_max_f32_e32 v35, v36, v37
	v_mul_f32_e32 v34, 0x41000000, v34
	v_mul_f32_e32 v34, v35, v34
	v_mul_f32_e32 v34, 0x3fb8aa3b, v34
	v_fmac_f32_e32 v241, 0x3f828f5c, v34
	v_mov_b64_e32 v[48:49], v[16:17]
	v_mov_b64_e32 v[46:47], v[14:15]
	v_mov_b64_e32 v[44:45], v[12:13]
	v_mov_b64_e32 v[42:43], v[10:11]
	v_mov_b64_e32 v[40:41], v[8:9]
	v_mov_b64_e32 v[38:39], v[6:7]
	v_mov_b64_e32 v[36:37], v[4:5]
	v_mov_b64_e32 v[34:35], v[2:3]
	v_mov_b64_e32 v[124:125], v[12:13]
	v_mov_b64_e32 v[122:123], v[10:11]
	v_mov_b64_e32 v[120:121], v[8:9]
	v_mov_b64_e32 v[118:119], v[6:7]
	v_mov_b64_e32 v[116:117], v[4:5]
	v_mov_b64_e32 v[114:115], v[2:3]
	v_mov_b32_e32 v243, 0x12dfc
	ds_read_b32 v241, v243
	s_waitcnt lgkmcnt(0)
	s_branch .LBB0_496
